# baseline (speedup 1.0000x reference)
;   __device__ __forceinline__ const float* in(int i) const { return reinterpret_cast<const float*>(ld64(i * 8)); }
;   __device__ __forceinline__ unsigned char* ws() const { return reinterpret_cast<unsigned char*>(ld64(27 * 8)); }
; __device__ __forceinline__ int opaque_tid() { int t = threadIdx.x; asm volatile("" : "+v"(t)); return t; }
; __device__ __forceinline__ void attn_diff(const bf16* __restrict__ Qg, const bf16* __restrict__ Kg, const bf16* __restrict__ Vg, int vts, ...
;     ...
;     for (int o = 1; o < 64; o <<= 1) { const float ta = __shfl_up(a, o), tc = __shfl_up(c, o); if (lane >= o) { a = fmaxf(a, ta); c = fmaxf(c, tc); } }
; __device__ __forceinline__ void phase_attention(const PRef& p, char* lds) {
;   const int tidx = opaque_tid();
;   unsigned* ctr = (unsigned*)(p.ws() + WS_CTR);
;   const int lane = tidx & 63;
;   float lam;
;   {
;     float a = p.in(13)[lane] * p.in(14)[lane], b = p.in(15)[lane] * p.in(16)[lane];
;     a = wave_sum(a); b = wave_sum(b);
;     lam = __expf(a) - __expf(b) + 0.2f;
;   }
;   bf16* Qb = (bf16*)(p.ws() + WS_Q);
;   volatile int* slot = (volatile int*)(lds + ATT_ITEM_OFF);
.LBB0_152:
	s_or_b64 exec, exec, s[0:1]
	v_readlane_b32 s0, v254, 5
	s_cmp_lg_u32 s0, -1
	s_cselect_b32 s4, s0, 0
	s_mov_b64 s[0:1], src_shared_base
	v_readlane_b32 s0, v254, 6
	s_cselect_b32 s5, s1, 0
	s_cmp_lg_u32 s0, -1
	v_mov_b32_e32 v6, v171
	v_mov_b64_e32 v[2:3], s[4:5]
	s_cselect_b32 s4, s0, 0
	s_cselect_b32 s5, s1, 0
	s_waitcnt lgkmcnt(0)
	s_barrier
	flat_load_dword v0, v[2:3] sc0 sc1
	s_waitcnt vmcnt(0)
	v_mov_b64_e32 v[4:5], s[4:5]
	flat_load_dword v7, v[4:5] sc0 sc1
	s_waitcnt vmcnt(0)
	s_mov_b64 s[76:77], 0
	s_waitcnt lgkmcnt(0)
	v_readfirstlane_b32 s0, v0
	s_add_u32 s6, s0, 0x2900000
	v_readfirstlane_b32 s4, v7
	s_addc_u32 s7, s4, 0
	s_add_i32 s0, 0, 0x23f68
	s_cmp_lg_u32 s0, -1
	s_cselect_b32 s0, s0, 0
	s_cselect_b32 s4, s1, 0
	v_mov_b32_e32 v8, s0
	s_add_i32 s0, 0, 0x23f6c
	s_cmp_lg_u32 s0, -1
	v_mov_b32_e32 v9, s4
	s_cselect_b32 s0, s0, 0
	s_cselect_b32 s4, s1, 0
	flat_load_dword v7, v[8:9] sc0 sc1
	s_waitcnt vmcnt(0)
	v_mov_b32_e32 v8, s0
	v_mov_b32_e32 v9, s4
	flat_load_dword v8, v[8:9] sc0 sc1
	s_waitcnt vmcnt(0)
	v_and_b32_e32 v0, 63, v6
	s_add_i32 s0, 0, 0x23f70
	v_lshlrev_b32_e32 v0, 2, v0
	s_cmp_lg_u32 s0, -1
	s_cselect_b32 s0, s0, 0
	v_writelane_b32 v254, s6, 57
	s_waitcnt lgkmcnt(0)
	v_readfirstlane_b32 s4, v7
	v_writelane_b32 v254, s7, 58
	v_readfirstlane_b32 s5, v8
	s_nop 1
	v_lshl_add_u64 v[8:9], s[4:5], 0, v[0:1]
	flat_load_dword v7, v[8:9]
	s_cselect_b32 s4, s1, 0
	v_mov_b32_e32 v8, s0
	s_add_i32 s0, 0, 0x23f74
	s_cmp_lg_u32 s0, -1
	v_mov_b32_e32 v9, s4
	s_cselect_b32 s0, s0, 0
	s_cselect_b32 s4, s1, 0
	flat_load_dword v10, v[8:9] sc0 sc1
	s_waitcnt vmcnt(0)
	v_mov_b32_e32 v8, s0
	v_mov_b32_e32 v9, s4
	flat_load_dword v8, v[8:9] sc0 sc1
	s_waitcnt vmcnt(0)
	s_add_i32 s0, 0, 0x23f78
	s_cmp_lg_u32 s0, -1
	s_cselect_b32 s0, s0, 0
	s_waitcnt lgkmcnt(0)
	v_readfirstlane_b32 s4, v10
	v_readfirstlane_b32 s5, v8
	s_nop 1
	v_lshl_add_u64 v[8:9], s[4:5], 0, v[0:1]
	flat_load_dword v10, v[8:9]
	s_cselect_b32 s4, s1, 0
	v_mov_b32_e32 v8, s0
	s_add_i32 s0, 0, 0x23f7c
	s_cmp_lg_u32 s0, -1
	v_mov_b32_e32 v9, s4
	s_cselect_b32 s0, s0, 0
	s_cselect_b32 s4, s1, 0
	flat_load_dword v12, v[8:9] sc0 sc1
	s_waitcnt vmcnt(0)
	v_mov_b32_e32 v8, s0
	v_mov_b32_e32 v9, s4
	flat_load_dword v8, v[8:9] sc0 sc1
	s_waitcnt vmcnt(0)
	s_add_i32 s0, 0, 0x23f80
	s_cmp_lg_u32 s0, -1
	s_cselect_b32 s0, s0, 0
	s_waitcnt lgkmcnt(0)
	v_mul_f32_e32 v11, v7, v10
	v_readfirstlane_b32 s4, v12
	v_readfirstlane_b32 s5, v8
	s_nop 1
	v_lshl_add_u64 v[8:9], s[4:5], 0, v[0:1]
	flat_load_dword v12, v[8:9]
	s_cselect_b32 s4, s1, 0
	v_mov_b32_e32 v8, s0
	s_add_i32 s0, 0, 0x23f84
	s_cmp_lg_u32 s0, -1
	v_mov_b32_e32 v9, s4
	s_cselect_b32 s0, s0, 0
	s_cselect_b32 s1, s1, 0
	flat_load_dword v13, v[8:9] sc0 sc1
	s_waitcnt vmcnt(0)
	v_mov_b32_e32 v8, s0
	v_mov_b32_e32 v9, s1
	flat_load_dword v8, v[8:9] sc0 sc1
	s_waitcnt vmcnt(0) lgkmcnt(0)
	v_readfirstlane_b32 s0, v13
	v_readfirstlane_b32 s1, v8
	s_nop 1
	v_lshl_add_u64 v[8:9], s[0:1], 0, v[0:1]
	flat_load_dword v0, v[8:9]
	v_xor_b32_e32 v9, 32, v193
	v_cmp_lt_i32_e32 vcc, v9, v195
	s_waitcnt vmcnt(0) lgkmcnt(0)
	v_mul_f32_e32 v8, v12, v0
	v_cndmask_b32_e32 v9, v193, v9, vcc
	v_lshlrev_b32_e32 v9, 2, v9
	ds_bpermute_b32 v11, v9, v11
	v_cmp_lt_i32_e32 vcc, v253, v195
	ds_bpermute_b32 v8, v9, v8
	s_waitcnt lgkmcnt(1)
	v_fmac_f32_e32 v11, v7, v10
	v_cndmask_b32_e32 v7, v193, v253, vcc
	v_lshlrev_b32_e32 v7, 2, v7
	ds_bpermute_b32 v10, v7, v11
	v_cmp_lt_i32_e32 vcc, v210, v195
	s_waitcnt lgkmcnt(1)
	v_fmac_f32_e32 v8, v12, v0
	ds_bpermute_b32 v0, v7, v8
	s_waitcnt lgkmcnt(1)
	v_add_f32_e32 v10, v11, v10
	v_cndmask_b32_e32 v11, v193, v210, vcc
	v_lshlrev_b32_e32 v11, 2, v11
	ds_bpermute_b32 v13, v11, v10
	s_waitcnt lgkmcnt(1)
	v_add_f32_e32 v0, v8, v0
	ds_bpermute_b32 v7, v11, v0
	s_waitcnt lgkmcnt(1)
	v_add_f32_e32 v10, v10, v13
	v_xor_b32_e32 v13, 4, v193
	v_cmp_lt_i32_e32 vcc, v13, v195
	s_waitcnt lgkmcnt(0)
	v_add_f32_e32 v0, v0, v7
	v_cndmask_b32_e32 v13, v193, v13, vcc
	v_lshlrev_b32_e32 v13, 2, v13
	ds_bpermute_b32 v14, v13, v10
	ds_bpermute_b32 v7, v13, v0
	s_waitcnt lgkmcnt(1)
	v_add_f32_e32 v10, v10, v14
	v_xor_b32_e32 v14, 2, v193
	v_cmp_lt_i32_e32 vcc, v14, v195
	s_waitcnt lgkmcnt(0)
	v_add_f32_e32 v0, v0, v7
	v_cndmask_b32_e32 v14, v193, v14, vcc
	v_lshlrev_b32_e32 v14, 2, v14
	ds_bpermute_b32 v15, v14, v10
	ds_bpermute_b32 v7, v14, v0
	s_waitcnt lgkmcnt(1)
	v_add_f32_e32 v10, v10, v15
	v_xor_b32_e32 v15, 1, v193
	v_cmp_lt_i32_e32 vcc, v15, v195
	s_waitcnt lgkmcnt(0)
	v_add_f32_e32 v0, v0, v7
	v_cndmask_b32_e32 v15, v193, v15, vcc
	v_lshlrev_b32_e32 v15, 2, v15
	ds_bpermute_b32 v16, v15, v10
	ds_bpermute_b32 v7, v15, v0
	s_waitcnt lgkmcnt(1)
	v_add_f32_e32 v10, v10, v16
	s_waitcnt lgkmcnt(0)
	v_add_f32_e32 v0, v0, v7
	v_mul_f32_e32 v7, 0x3fb8aa3b, v10
	v_mul_f32_e32 v0, 0x3fb8aa3b, v0
	v_exp_f32_e32 v7, v7
	v_exp_f32_e32 v0, v0
	s_nop 0
	v_sub_f32_e32 v0, v7, v0
	v_add_f32_e32 v146, 0x3e4ccccd, v0
	flat_load_dword v0, v[2:3] sc0 sc1
	s_waitcnt vmcnt(0)
	flat_load_dword v2, v[4:5] sc0 sc1
	s_waitcnt vmcnt(0)
	v_mov_b32_e32 v147, v146
	s_waitcnt lgkmcnt(0)
	v_readfirstlane_b32 s0, v0
	v_readfirstlane_b32 s1, v2
	v_add_u32_e32 v0, -1, v193
	v_and_b32_e32 v2, 64, v193
	v_cmp_lt_i32_e32 vcc, v0, v2
	s_add_u32 s0, s0, 0x8c00000
	s_addc_u32 s1, s1, 0
	v_cndmask_b32_e32 v0, v0, v193, vcc
	v_lshlrev_b32_e32 v212, 2, v0
	v_add_u32_e32 v0, -2, v193
	v_cmp_lt_i32_e32 vcc, v0, v2
	v_writelane_b32 v254, s0, 59
	s_nop 0
	v_cndmask_b32_e32 v0, v0, v193, vcc
	v_lshlrev_b32_e32 v213, 2, v0
	v_add_u32_e32 v0, -4, v193
	v_cmp_lt_i32_e32 vcc, v0, v2
	v_writelane_b32 v254, s1, 60
	v_cmp_eq_u32_e64 s[0:1], 0, v6
	v_cndmask_b32_e32 v0, v0, v193, vcc
	v_lshlrev_b32_e32 v214, 2, v0
	v_add_u32_e32 v0, -8, v193
	v_cmp_lt_i32_e32 vcc, v0, v2
	v_writelane_b32 v254, s0, 61
	s_nop 0
	v_cndmask_b32_e32 v0, v0, v193, vcc
	v_lshlrev_b32_e32 v215, 2, v0
	v_add_u32_e32 v0, -16, v193
	v_cmp_lt_i32_e32 vcc, v0, v2
	v_writelane_b32 v254, s1, 62
	s_nop 0
	v_cndmask_b32_e32 v0, v0, v193, vcc
	v_lshlrev_b32_e32 v216, 2, v0
	v_subrev_u32_e32 v0, 32, v193
	v_cmp_lt_i32_e32 vcc, v0, v2
	s_nop 1
	v_cndmask_b32_e32 v0, v0, v193, vcc
	v_lshlrev_b32_e32 v217, 2, v0
	v_bfrev_b32_e32 v0, 0.5
	v_lshl_or_b32 v218, v193, 2, v0
	s_mov_b32 s100, 1
	s_branch .LBB0_157

; __device__ __forceinline__ void phase_attention(const PRef& p, char* lds) {
;     ...
;   for (;;) {
;     if (tidx == 0) *slot = (int)atomicAdd(ctr, 1u);
;     __syncthreads();
;     const int item = *slot;
.LBB0_157:
	s_mov_b64 s[0:1], exec
	v_readlane_b32 s4, v254, 61
	v_readlane_b32 s5, v254, 62
	s_and_b64 s[4:5], s[0:1], s[4:5]
	s_mov_b64 exec, s[4:5]
	s_cbranch_execz .LBB0_159
	v_readlane_b32 s6, v254, 57
	v_readlane_b32 s7, v254, 58
	s_mov_b64 s[4:5], src_shared_base
	s_add_i32 s4, 0, 0x22000
	v_mov_b64_e32 v[2:3], s[6:7]
	s_cmp_lg_u32 s100, 0
	s_cbranch_scc1 .Lmy_dq_first
	flat_atomic_add v0, v[2:3], v191 sc0
	v_readlane_b32 s6, v254, 1
	s_waitcnt vmcnt(0) lgkmcnt(0)
	s_nop 1
	v_add_u32_e32 v0, s6, v0
	s_branch .Lmy_dq_have
.Lmy_dq_first:
	s_mov_b32 s100, 0
	v_readlane_b32 s6, v254, 0
	s_nop 3
	v_mov_b32_e32 v0, s6
.Lmy_dq_have:
	s_cmp_lg_u32 s4, -1
	s_cselect_b32 s4, s4, 0
	s_cselect_b32 s5, s5, 0
	v_mov_b32_e32 v2, s4
	v_mov_b32_e32 v3, s5
	s_waitcnt vmcnt(0) lgkmcnt(0)
	flat_store_dword v[2:3], v0 sc0 sc1
	s_waitcnt vmcnt(0)
